# split barriers: thread 0 samples the barrier generation word from inside the transpose slice (right after the tile LDS barrier), so the wait polls only if that sample was still old
# speedup vs baseline: 1.0123x; 1.0055x over previous
.LBB0_126:
	v_mov_b32_e32 v201, 0x24008
	ds_read_b32 v200, v201
	s_waitcnt lgkmcnt(0)
	s_cmp_lt_i32 s88, 1
	s_cbranch_scc0 .Lsl0_out
	s_cmp_gt_i32 s89, 0
	s_cbranch_scc0 .Lsl0_out
	s_load_dword s4, s[0:1], 0x120
	s_load_dwordx16 s[52:67], s[0:1], 0x0
	s_load_dwordx16 s[68:83], s[0:1], 0x80
	s_waitcnt lgkmcnt(0)
	s_add_u32 s98, s34, 0xed10500
	s_addc_u32 s99, s35, 0
	v_mov_b32_e32 v201, 0
	s_lshl_b32 s4, s4, 1
	s_mul_i32 s5, s4, 1
	s_lshl_b32 s33, s2, 1
	s_add_i32 s33, s33, s5
	s_cmp_eq_u32 s89, 18
	s_cselect_b32 s5, 3, 11
	s_mul_i32 s4, s4, s5
	s_min_u32 s4, s4, 0x15d0
	s_cmp_ge_i32 s33, s4
	s_cbranch_scc1 .Lsl0_out
	s_add_u32 s94, s34, 0x1da0000
	s_addc_u32 s95, s35, 0
	v_writelane_b32 v252, s90, 0
	s_add_u32 s4, s34, 0x7a0000
	s_addc_u32 s5, s35, 0
	v_writelane_b32 v252, s91, 1
	v_writelane_b32 v252, s4, 2
	v_lshrrev_b32_e32 v138, 8, v204
	v_and_b32_e32 v139, 0xff, v204
	v_writelane_b32 v252, s5, 3
	s_add_u32 s4, s34, 0x720000
	s_addc_u32 s5, s35, 0
	v_writelane_b32 v252, s4, 4
	v_mul_u32_u24_e32 v140, 0x12000, v138
	v_mov_b32_e32 v129, 0
	v_writelane_b32 v252, s5, 5
	s_add_u32 s4, s34, 0x520000
	s_addc_u32 s5, s35, 0
	s_add_u32 s90, s34, 0x4a0000
	s_addc_u32 s91, s35, 0
	s_add_u32 s96, s34, 0x440000
	s_addc_u32 s97, s35, 0
	s_add_u32 s16, s34, 0x28a0000
	s_addc_u32 s17, s35, 0
	s_add_u32 s18, s0, 0x120
	v_writelane_b32 v252, s4, 6
	s_addc_u32 s19, s1, 0
	s_movk_i32 s8, 0x104
	s_movk_i32 s9, 0xffe0
	s_movk_i32 s10, 0x6000
	s_movk_i32 s11, 0x400
	s_mov_b32 s12, 0xbfb8aa3b
	s_mov_b32 s13, 0x42ce8ed0
	s_mov_b32 s14, 0xc2b17218
	s_movk_i32 s15, 0x1800
	v_mov_b32_e32 v141, 0xfffffd40
	v_mov_b32_e32 v142, 0xb00000
	v_mov_b32_e32 v143, 0x580000
	v_mov_b32_e32 v144, 0x7f800000
	v_writelane_b32 v252, s5, 7
	s_branch .Lsl0_22

.Lsl0_49:
	s_or_b64 exec, exec, s[20:21]
	v_cvt_f32_i32_sdwa v12, sext(v9) dst_sel:DWORD dst_unused:UNUSED_PAD src0_sel:WORD_0
	v_cvt_f32_i32_sdwa v11, sext(v6) dst_sel:DWORD dst_unused:UNUSED_PAD src0_sel:WORD_0
	v_xor_b32_sdwa v10, sext(v6), sext(v9) dst_sel:DWORD dst_unused:UNUSED_PAD src0_sel:WORD_0 src1_sel:WORD_0
	v_ashrrev_i32_e32 v10, 30, v10
	v_rcp_iflag_f32_e32 v13, v12
	v_or_b32_e32 v10, 1, v10
	v_and_b32_e32 v14, 63, v8
	v_ashrrev_i32_e32 v15, 6, v8
	v_mul_f32_e32 v13, v11, v13
	v_trunc_f32_e32 v13, v13
	v_fma_f32 v11, -v13, v12, v11
	v_cvt_i32_f32_e32 v13, v13
	v_cmp_ge_f32_e64 vcc, |v11|, |v12|
	s_nop 1
	v_cndmask_b32_e32 v10, 0, v10, vcc
	v_add_u32_e32 v10, v13, v10
	v_bfe_i32 v10, v10, 0, 16
	v_mul_lo_u32 v9, v9, v10
	v_sub_u32_e32 v9, v6, v9
	v_lshlrev_b32_e32 v9, 6, v9
	v_lshlrev_b32_e32 v6, 6, v10
	v_or_b32_e32 v16, v9, v14
	v_add_u32_e32 v10, -1, v7
	v_min_i32_e32 v10, v16, v10
	v_add_u32_e32 v17, v6, v15
	v_ashrrev_i32_e32 v11, 31, v10
	v_lshl_add_u64 v[4:5], v[10:11], 2, v[4:5]
	v_mad_u64_u32 v[10:11], s[20:21], v17, v7, 0
	v_ashrrev_i32_e32 v13, 31, v17
	v_mov_b32_e32 v12, v11
	v_mad_u64_u32 v[12:13], s[20:21], v13, v7, v[12:13]
	v_mov_b32_e32 v11, v12
	v_lshl_add_u64 v[10:11], v[10:11], 2, v[4:5]
	global_load_dword v18, v[10:11], off nt
	v_add_u32_e32 v10, 4, v17
	v_ashrrev_i32_e32 v13, 31, v10
	v_mad_u64_u32 v[10:11], s[20:21], v10, v7, 0
	v_mov_b32_e32 v12, v11
	v_mad_u64_u32 v[12:13], s[20:21], v13, v7, v[12:13]
	v_mov_b32_e32 v11, v12
	v_lshl_add_u64 v[10:11], v[10:11], 2, v[4:5]
	global_load_dword v19, v[10:11], off nt
	v_add_u32_e32 v10, 8, v17
	v_ashrrev_i32_e32 v13, 31, v10
	v_mad_u64_u32 v[10:11], s[20:21], v10, v7, 0
	v_mov_b32_e32 v12, v11
	v_mad_u64_u32 v[12:13], s[20:21], v13, v7, v[12:13]
	v_mov_b32_e32 v11, v12
	v_lshl_add_u64 v[10:11], v[10:11], 2, v[4:5]
	global_load_dword v20, v[10:11], off nt
	v_add_u32_e32 v10, 12, v17
	v_ashrrev_i32_e32 v13, 31, v10
	v_mad_u64_u32 v[10:11], s[20:21], v10, v7, 0
	v_mov_b32_e32 v12, v11
	v_mad_u64_u32 v[12:13], s[20:21], v13, v7, v[12:13]
	v_mov_b32_e32 v11, v12
	v_lshl_add_u64 v[10:11], v[10:11], 2, v[4:5]
	global_load_dword v21, v[10:11], off nt
	v_add_u32_e32 v10, 16, v17
	v_ashrrev_i32_e32 v13, 31, v10
	v_mad_u64_u32 v[10:11], s[20:21], v10, v7, 0
	v_mov_b32_e32 v12, v11
	v_mad_u64_u32 v[12:13], s[20:21], v13, v7, v[12:13]
	v_mov_b32_e32 v11, v12
	v_lshl_add_u64 v[10:11], v[10:11], 2, v[4:5]
	global_load_dword v22, v[10:11], off nt
	v_add_u32_e32 v10, 20, v17
	v_ashrrev_i32_e32 v13, 31, v10
	v_mad_u64_u32 v[10:11], s[20:21], v10, v7, 0
	v_mov_b32_e32 v12, v11
	v_mad_u64_u32 v[12:13], s[20:21], v13, v7, v[12:13]
	v_mov_b32_e32 v11, v12
	v_lshl_add_u64 v[10:11], v[10:11], 2, v[4:5]
	global_load_dword v23, v[10:11], off nt
	v_add_u32_e32 v10, 24, v17
	v_ashrrev_i32_e32 v13, 31, v10
	v_mad_u64_u32 v[10:11], s[20:21], v10, v7, 0
	v_mov_b32_e32 v12, v11
	v_mad_u64_u32 v[12:13], s[20:21], v13, v7, v[12:13]
	v_mov_b32_e32 v11, v12
	v_lshl_add_u64 v[10:11], v[10:11], 2, v[4:5]
	global_load_dword v24, v[10:11], off nt
	v_add_u32_e32 v10, 28, v17
	v_ashrrev_i32_e32 v13, 31, v10
	v_mad_u64_u32 v[10:11], s[20:21], v10, v7, 0
	v_mov_b32_e32 v12, v11
	v_mad_u64_u32 v[12:13], s[20:21], v13, v7, v[12:13]
	v_mov_b32_e32 v11, v12
	v_lshl_add_u64 v[10:11], v[10:11], 2, v[4:5]
	global_load_dword v25, v[10:11], off nt
	v_add_u32_e32 v10, 32, v17
	v_ashrrev_i32_e32 v13, 31, v10
	v_mad_u64_u32 v[10:11], s[20:21], v10, v7, 0
	v_mov_b32_e32 v12, v11
	v_mad_u64_u32 v[12:13], s[20:21], v13, v7, v[12:13]
	v_mov_b32_e32 v11, v12
	v_lshl_add_u64 v[10:11], v[10:11], 2, v[4:5]
	global_load_dword v26, v[10:11], off nt
	v_add_u32_e32 v10, 36, v17
	v_ashrrev_i32_e32 v13, 31, v10
	v_mad_u64_u32 v[10:11], s[20:21], v10, v7, 0
	v_mov_b32_e32 v12, v11
	v_mad_u64_u32 v[12:13], s[20:21], v13, v7, v[12:13]
	v_mov_b32_e32 v11, v12
	v_lshl_add_u64 v[10:11], v[10:11], 2, v[4:5]
	global_load_dword v27, v[10:11], off nt
	v_add_u32_e32 v10, 40, v17
	v_ashrrev_i32_e32 v13, 31, v10
	v_mad_u64_u32 v[10:11], s[20:21], v10, v7, 0
	v_mov_b32_e32 v12, v11
	v_mad_u64_u32 v[12:13], s[20:21], v13, v7, v[12:13]
	v_mov_b32_e32 v11, v12
	v_lshl_add_u64 v[10:11], v[10:11], 2, v[4:5]
	global_load_dword v28, v[10:11], off nt
	v_add_u32_e32 v10, 44, v17
	v_ashrrev_i32_e32 v13, 31, v10
	v_mad_u64_u32 v[10:11], s[20:21], v10, v7, 0
	v_mov_b32_e32 v12, v11
	v_mad_u64_u32 v[12:13], s[20:21], v13, v7, v[12:13]
	v_mov_b32_e32 v11, v12
	v_lshl_add_u64 v[10:11], v[10:11], 2, v[4:5]
	global_load_dword v29, v[10:11], off nt
	v_add_u32_e32 v10, 48, v17
	v_ashrrev_i32_e32 v13, 31, v10
	v_mad_u64_u32 v[10:11], s[20:21], v10, v7, 0
	v_mov_b32_e32 v12, v11
	v_mad_u64_u32 v[12:13], s[20:21], v13, v7, v[12:13]
	v_mov_b32_e32 v11, v12
	v_lshl_add_u64 v[10:11], v[10:11], 2, v[4:5]
	global_load_dword v30, v[10:11], off nt
	v_add_u32_e32 v10, 52, v17
	v_ashrrev_i32_e32 v13, 31, v10
	v_mad_u64_u32 v[10:11], s[20:21], v10, v7, 0
	v_mov_b32_e32 v12, v11
	v_mad_u64_u32 v[12:13], s[20:21], v13, v7, v[12:13]
	v_mov_b32_e32 v11, v12
	v_lshl_add_u64 v[10:11], v[10:11], 2, v[4:5]
	global_load_dword v31, v[10:11], off nt
	v_add_u32_e32 v10, 56, v17
	v_ashrrev_i32_e32 v13, 31, v10
	v_mad_u64_u32 v[10:11], s[20:21], v10, v7, 0
	v_mov_b32_e32 v12, v11
	v_mad_u64_u32 v[12:13], s[20:21], v13, v7, v[12:13]
	v_mov_b32_e32 v11, v12
	v_lshl_add_u64 v[10:11], v[10:11], 2, v[4:5]
	global_load_dword v32, v[10:11], off nt
	v_add_u32_e32 v10, 60, v17
	v_ashrrev_i32_e32 v13, 31, v10
	v_mad_u64_u32 v[10:11], s[20:21], v10, v7, 0
	v_mov_b32_e32 v12, v11
	v_mad_u64_u32 v[12:13], s[20:21], v13, v7, v[12:13]
	v_mov_b32_e32 v11, v12
	v_lshl_add_u64 v[4:5], v[10:11], 2, v[4:5]
	global_load_dword v4, v[4:5], off nt
	v_cmp_lt_i32_e32 vcc, v16, v7
	v_lshlrev_b32_e32 v5, 2, v14
	v_mul_lo_u32 v10, v15, s8
	s_waitcnt vmcnt(15)
	v_cndmask_b32_e32 v7, 0, v18, vcc
	v_add3_u32 v5, v140, v5, v10
	ds_write_b32 v5, v7
	s_waitcnt vmcnt(14)
	v_cndmask_b32_e32 v7, 0, v19, vcc
	ds_write_b32 v5, v7 offset:1040
	s_waitcnt vmcnt(13)
	v_cndmask_b32_e32 v7, 0, v20, vcc
	ds_write_b32 v5, v7 offset:2080
	s_waitcnt vmcnt(12)
	v_cndmask_b32_e32 v7, 0, v21, vcc
	ds_write_b32 v5, v7 offset:3120
	s_waitcnt vmcnt(11)
	v_cndmask_b32_e32 v7, 0, v22, vcc
	ds_write_b32 v5, v7 offset:4160
	s_waitcnt vmcnt(10)
	v_cndmask_b32_e32 v7, 0, v23, vcc
	ds_write_b32 v5, v7 offset:5200
	s_waitcnt vmcnt(9)
	v_cndmask_b32_e32 v7, 0, v24, vcc
	ds_write_b32 v5, v7 offset:6240
	s_waitcnt vmcnt(8)
	v_cndmask_b32_e32 v7, 0, v25, vcc
	ds_write_b32 v5, v7 offset:7280
	s_waitcnt vmcnt(7)
	v_cndmask_b32_e32 v7, 0, v26, vcc
	ds_write_b32 v5, v7 offset:8320
	s_waitcnt vmcnt(6)
	v_cndmask_b32_e32 v7, 0, v27, vcc
	ds_write_b32 v5, v7 offset:9360
	v_ashrrev_i32_e32 v13, 3, v8
	v_add_u32_e32 v14, v9, v13
	s_waitcnt vmcnt(5)
	v_cndmask_b32_e32 v7, 0, v28, vcc
	ds_write_b32 v5, v7 offset:10400
	s_waitcnt vmcnt(4)
	v_cndmask_b32_e32 v7, 0, v29, vcc
	ds_write_b32 v5, v7 offset:11440
	s_waitcnt vmcnt(3)
	v_cndmask_b32_e32 v7, 0, v30, vcc
	ds_write_b32 v5, v7 offset:12480
	s_waitcnt vmcnt(2)
	v_cndmask_b32_e32 v7, 0, v31, vcc
	ds_write_b32 v5, v7 offset:13520
	s_waitcnt vmcnt(1)
	v_cndmask_b32_e32 v7, 0, v32, vcc
	ds_write_b32 v5, v7 offset:14560
	v_ashrrev_i32_e32 v7, 31, v6
	v_lshl_add_u64 v[2:3], v[6:7], 1, v[2:3]
	s_waitcnt vmcnt(0)
	v_cndmask_b32_e32 v4, 0, v4, vcc
	ds_write_b32 v5, v4 offset:15600
	v_lshlrev_b32_e32 v4, 3, v8
	v_and_b32_e32 v4, 56, v4
	v_mad_u32_u24 v12, v4, s8, v140
	v_lshlrev_b32_e32 v128, 1, v4
	v_lshl_add_u32 v10, v13, 2, v12
	s_waitcnt lgkmcnt(0)
	s_barrier
	s_and_saveexec_b64 s[100:101], s[92:93]
	global_load_dword v200, v201, s[98:99] sc1
	s_mov_b64 exec, s[100:101]
	v_lshl_add_u64 v[6:7], v[2:3], 0, v[128:129]
	ds_read2_b32 v[2:3], v10 offset1:65
	ds_read2_b32 v[4:5], v10 offset0:130 offset1:195
	v_add_u32_e32 v10, 0x400, v10
	s_waitcnt lgkmcnt(1)
	v_cvt_pk_bf16_f32 v2, v2, v3
	s_waitcnt lgkmcnt(0)
	v_cvt_pk_bf16_f32 v3, v4, v5
	ds_read2_b32 v[4:5], v10 offset0:4 offset1:69
	ds_read2_b32 v[10:11], v10 offset0:134 offset1:199
	s_waitcnt lgkmcnt(1)
	v_cvt_pk_bf16_f32 v4, v4, v5
	s_waitcnt lgkmcnt(0)
	v_cvt_pk_bf16_f32 v5, v10, v11
	v_lshlrev_b32_e32 v10, 1, v14
	v_and_b32_e32 v11, 15, v13
	v_and_or_b32 v10, v10, s9, v11
	v_or_b32_e32 v11, 16, v10
	v_cndmask_b32_e64 v11, v14, v11, s[22:23]
	v_cndmask_b32_e64 v10, v11, v10, s[24:25]
	v_ashrrev_i32_e32 v11, 31, v10
	v_mul_lo_u32 v13, v0, v11
	v_mul_lo_u32 v14, v1, v10
	v_mad_u64_u32 v[10:11], s[20:21], v0, v10, 0
	v_add3_u32 v11, v11, v13, v14
	v_lshl_add_u64 v[10:11], v[10:11], 1, v[6:7]
	global_store_dwordx4 v[10:11], v[2:5], off
	s_nop 1
	v_add_u32_e32 v2, 0x100, v8
	v_ashrrev_i32_e32 v13, 3, v2
	v_add_u32_e32 v14, v9, v13
	v_lshl_add_u32 v4, v13, 2, v12
	ds_read2_b32 v[8:9], v4 offset1:65
	ds_read2_b32 v[2:3], v4 offset0:130 offset1:195
	v_lshlrev_b32_e32 v12, 1, v14
	v_and_b32_e32 v13, 15, v13
	v_and_or_b32 v12, v12, s9, v13
	v_add_u32_e32 v4, 0x400, v4
	v_or_b32_e32 v13, 16, v12
	ds_read2_b32 v[10:11], v4 offset0:4 offset1:69
	ds_read2_b32 v[4:5], v4 offset0:134 offset1:199
	v_cndmask_b32_e64 v13, v14, v13, s[22:23]
	v_cndmask_b32_e64 v12, v13, v12, s[24:25]
	s_waitcnt lgkmcnt(2)
	v_cvt_pk_bf16_f32 v3, v2, v3
	v_cvt_pk_bf16_f32 v2, v8, v9
	v_ashrrev_i32_e32 v8, 31, v12
	v_mul_lo_u32 v8, v0, v8
	v_mul_lo_u32 v9, v1, v12
	v_mad_u64_u32 v[0:1], s[20:21], v0, v12, 0
	v_add3_u32 v1, v1, v8, v9
	s_waitcnt lgkmcnt(0)
	v_cvt_pk_bf16_f32 v5, v4, v5
	v_cvt_pk_bf16_f32 v4, v10, v11
	v_lshl_add_u64 v[0:1], v[0:1], 1, v[6:7]
	global_store_dwordx4 v[0:1], v[2:5], off
	s_barrier

.Lsl0_out:
	s_cmp_gt_i32 s88, 0
	s_cbranch_scc1 .Lsb0_skip
	s_cmp_lt_i32 s89, 2
	s_cbranch_scc1 .Lsb0_skip
	s_waitcnt vmcnt(0) lgkmcnt(0)
	s_and_saveexec_b64 s[16:17], s[92:93]
	s_cbranch_execz .Lsb0_done
	v_mov_b32_e32 v0, 0x24008
	ds_read_b32 v1, v0
	buffer_inv sc1
	s_add_u32 s18, s34, 0xed10500
	s_addc_u32 s19, s35, 0
	v_mov_b32_e32 v0, 0
	s_mov_b32 s20, 0
	s_waitcnt lgkmcnt(0)
	v_cmp_eq_u32_e32 vcc, v200, v1
	s_cbranch_vccz .Lsb0_done

.LBB0_189:
	v_mov_b32_e32 v201, 0x24008
	ds_read_b32 v200, v201
	s_waitcnt lgkmcnt(0)
	s_cmp_lg_u32 s88, 0
	s_cbranch_scc1 .Lsl1_out
	s_cmp_lg_u32 s89, 18
	s_cbranch_scc1 .Lsl1_out
	s_load_dword s4, s[0:1], 0x120
	s_load_dwordx16 s[52:67], s[0:1], 0x0
	s_load_dwordx16 s[68:83], s[0:1], 0x80
	s_waitcnt lgkmcnt(0)
	s_add_u32 s98, s34, 0xed10500
	s_addc_u32 s99, s35, 0
	v_mov_b32_e32 v201, 0
	s_lshl_b32 s4, s4, 1
	s_mul_i32 s5, s4, 3
	s_lshl_b32 s33, s2, 1
	s_add_i32 s33, s33, s5
	s_mov_b32 s5, 4
	s_mul_i32 s4, s4, s5
	s_min_u32 s4, s4, 0x15d0
	s_cmp_ge_i32 s33, s4
	s_cbranch_scc1 .Lsl1_out
	s_add_u32 s94, s34, 0x1da0000
	s_addc_u32 s95, s35, 0
	v_writelane_b32 v252, s90, 0
	s_add_u32 s4, s34, 0x7a0000
	s_addc_u32 s5, s35, 0
	v_writelane_b32 v252, s91, 1
	v_writelane_b32 v252, s4, 2
	v_lshrrev_b32_e32 v138, 8, v204
	v_and_b32_e32 v139, 0xff, v204
	v_writelane_b32 v252, s5, 3
	s_add_u32 s4, s34, 0x720000
	s_addc_u32 s5, s35, 0
	v_writelane_b32 v252, s4, 4
	v_mul_u32_u24_e32 v140, 0x12000, v138
	v_mov_b32_e32 v129, 0
	v_writelane_b32 v252, s5, 5
	s_add_u32 s4, s34, 0x520000
	s_addc_u32 s5, s35, 0
	s_add_u32 s90, s34, 0x4a0000
	s_addc_u32 s91, s35, 0
	s_add_u32 s96, s34, 0x440000
	s_addc_u32 s97, s35, 0
	s_add_u32 s16, s34, 0x28a0000
	s_addc_u32 s17, s35, 0
	s_add_u32 s18, s0, 0x120
	v_writelane_b32 v252, s4, 6
	s_addc_u32 s19, s1, 0
	s_movk_i32 s8, 0x104
	s_movk_i32 s9, 0xffe0
	s_movk_i32 s10, 0x6000
	s_movk_i32 s11, 0x400
	s_mov_b32 s12, 0xbfb8aa3b
	s_mov_b32 s13, 0x42ce8ed0
	s_mov_b32 s14, 0xc2b17218
	s_movk_i32 s15, 0x1800
	v_mov_b32_e32 v141, 0xfffffd40
	v_mov_b32_e32 v142, 0xb00000
	v_mov_b32_e32 v143, 0x580000
	v_mov_b32_e32 v144, 0x7f800000
	v_writelane_b32 v252, s5, 7
	s_branch .Lsl1_22

.Lsl1_out:
	s_cmp_gt_i32 s88, 1
	s_cbranch_scc1 .Lsb1_skip
	s_cmp_lt_i32 s89, 3
	s_cbranch_scc1 .Lsb1_skip
	s_waitcnt vmcnt(0) lgkmcnt(0)
	s_and_saveexec_b64 s[16:17], s[92:93]
	s_cbranch_execz .Lsb1_done
	v_mov_b32_e32 v0, 0x24008
	ds_read_b32 v1, v0
	buffer_inv sc1
	s_add_u32 s18, s34, 0xed10500
	s_addc_u32 s19, s35, 0
	v_mov_b32_e32 v0, 0
	s_mov_b32 s20, 0
	s_waitcnt lgkmcnt(0)
	v_cmp_eq_u32_e32 vcc, v200, v1
	s_cbranch_vccz .Lsb1_done

.LBB0_480:
	v_mov_b32_e32 v201, 0x24008
	ds_read_b32 v200, v201
	s_waitcnt lgkmcnt(0)
	s_cmp_lg_u32 s88, 0
	s_cbranch_scc1 .Lsl2_out
	s_cmp_lg_u32 s89, 18
	s_cbranch_scc1 .Lsl2_out
	s_load_dword s4, s[0:1], 0x120
	s_load_dwordx16 s[52:67], s[0:1], 0x0
	s_load_dwordx16 s[68:83], s[0:1], 0x80
	s_waitcnt lgkmcnt(0)
	s_add_u32 s98, s34, 0xed10500
	s_addc_u32 s99, s35, 0
	v_mov_b32_e32 v201, 0
	s_lshl_b32 s4, s4, 1
	s_mul_i32 s5, s4, 4
	s_lshl_b32 s33, s2, 1
	s_add_i32 s33, s33, s5
	s_mov_b32 s5, 5
	s_mul_i32 s4, s4, s5
	s_min_u32 s4, s4, 0x15d0
	s_cmp_ge_i32 s33, s4
	s_cbranch_scc1 .Lsl2_out
	s_add_u32 s94, s34, 0x1da0000
	s_addc_u32 s95, s35, 0
	v_writelane_b32 v252, s90, 0
	s_add_u32 s4, s34, 0x7a0000
	s_addc_u32 s5, s35, 0
	v_writelane_b32 v252, s91, 1
	v_writelane_b32 v252, s4, 2
	v_lshrrev_b32_e32 v138, 8, v204
	v_and_b32_e32 v139, 0xff, v204
	v_writelane_b32 v252, s5, 3
	s_add_u32 s4, s34, 0x720000
	s_addc_u32 s5, s35, 0
	v_writelane_b32 v252, s4, 4
	v_mul_u32_u24_e32 v140, 0x12000, v138
	v_mov_b32_e32 v129, 0
	v_writelane_b32 v252, s5, 5
	s_add_u32 s4, s34, 0x520000
	s_addc_u32 s5, s35, 0
	s_add_u32 s90, s34, 0x4a0000
	s_addc_u32 s91, s35, 0
	s_add_u32 s96, s34, 0x440000
	s_addc_u32 s97, s35, 0
	s_add_u32 s16, s34, 0x28a0000
	s_addc_u32 s17, s35, 0
	s_add_u32 s18, s0, 0x120
	v_writelane_b32 v252, s4, 6
	s_addc_u32 s19, s1, 0
	s_movk_i32 s8, 0x104
	s_movk_i32 s9, 0xffe0
	s_movk_i32 s10, 0x6000
	s_movk_i32 s11, 0x400
	s_mov_b32 s12, 0xbfb8aa3b
	s_mov_b32 s13, 0x42ce8ed0
	s_mov_b32 s14, 0xc2b17218
	s_movk_i32 s15, 0x1800
	v_mov_b32_e32 v141, 0xfffffd40
	v_mov_b32_e32 v142, 0xb00000
	v_mov_b32_e32 v143, 0x580000
	v_mov_b32_e32 v144, 0x7f800000
	v_writelane_b32 v252, s5, 7
	s_branch .Lsl2_22

.Lsl2_out:
	s_cmp_gt_i32 s88, 2
	s_cbranch_scc1 .Lsb2_skip
	s_cmp_lt_i32 s89, 4
	s_cbranch_scc1 .Lsb2_skip
	s_waitcnt vmcnt(0) lgkmcnt(0)
	s_and_saveexec_b64 s[16:17], s[92:93]
	s_cbranch_execz .Lsb2_done
	v_mov_b32_e32 v0, 0x24008
	ds_read_b32 v1, v0
	buffer_inv sc1
	s_add_u32 s18, s34, 0xed10500
	s_addc_u32 s19, s35, 0
	v_mov_b32_e32 v0, 0
	s_mov_b32 s20, 0
	s_waitcnt lgkmcnt(0)
	v_cmp_eq_u32_e32 vcc, v200, v1
	s_cbranch_vccz .Lsb2_done

.LBB0_615:
	v_mov_b32_e32 v201, 0x24008
	ds_read_b32 v200, v201
	s_waitcnt lgkmcnt(0)
	s_cmp_lg_u32 s88, 0
	s_cbranch_scc1 .Lsl3_out
	s_cmp_lg_u32 s89, 18
	s_cbranch_scc1 .Lsl3_out
	s_load_dword s4, s[0:1], 0x120
	s_load_dwordx16 s[52:67], s[0:1], 0x0
	s_load_dwordx16 s[68:83], s[0:1], 0x80
	s_waitcnt lgkmcnt(0)
	s_add_u32 s98, s34, 0xed10500
	s_addc_u32 s99, s35, 0
	v_mov_b32_e32 v201, 0
	s_lshl_b32 s4, s4, 1
	s_mul_i32 s5, s4, 5
	s_lshl_b32 s33, s2, 1
	s_add_i32 s33, s33, s5
	s_mov_b32 s5, 6
	s_mul_i32 s4, s4, s5
	s_min_u32 s4, s4, 0x15d0
	s_cmp_ge_i32 s33, s4
	s_cbranch_scc1 .Lsl3_out
	s_add_u32 s94, s34, 0x1da0000
	s_addc_u32 s95, s35, 0
	v_writelane_b32 v252, s90, 0
	s_add_u32 s4, s34, 0x7a0000
	s_addc_u32 s5, s35, 0
	v_writelane_b32 v252, s91, 1
	v_writelane_b32 v252, s4, 2
	v_lshrrev_b32_e32 v138, 8, v204
	v_and_b32_e32 v139, 0xff, v204
	v_writelane_b32 v252, s5, 3
	s_add_u32 s4, s34, 0x720000
	s_addc_u32 s5, s35, 0
	v_writelane_b32 v252, s4, 4
	v_mul_u32_u24_e32 v140, 0x12000, v138
	v_mov_b32_e32 v129, 0
	v_writelane_b32 v252, s5, 5
	s_add_u32 s4, s34, 0x520000
	s_addc_u32 s5, s35, 0
	s_add_u32 s90, s34, 0x4a0000
	s_addc_u32 s91, s35, 0
	s_add_u32 s96, s34, 0x440000
	s_addc_u32 s97, s35, 0
	s_add_u32 s16, s34, 0x28a0000
	s_addc_u32 s17, s35, 0
	s_add_u32 s18, s0, 0x120
	v_writelane_b32 v252, s4, 6
	s_addc_u32 s19, s1, 0
	s_movk_i32 s8, 0x104
	s_movk_i32 s9, 0xffe0
	s_movk_i32 s10, 0x6000
	s_movk_i32 s11, 0x400
	s_mov_b32 s12, 0xbfb8aa3b
	s_mov_b32 s13, 0x42ce8ed0
	s_mov_b32 s14, 0xc2b17218
	s_movk_i32 s15, 0x1800
	v_mov_b32_e32 v141, 0xfffffd40
	v_mov_b32_e32 v142, 0xb00000
	v_mov_b32_e32 v143, 0x580000
	v_mov_b32_e32 v144, 0x7f800000
	v_writelane_b32 v252, s5, 7
	s_branch .Lsl3_22

.Lsl3_out:
	s_cmp_gt_i32 s88, 3
	s_cbranch_scc1 .Lsb3_skip
	s_cmp_lt_i32 s89, 5
	s_cbranch_scc1 .Lsb3_skip
	s_waitcnt vmcnt(0) lgkmcnt(0)
	s_and_saveexec_b64 s[16:17], s[92:93]
	s_cbranch_execz .Lsb3_done
	v_mov_b32_e32 v0, 0x24008
	ds_read_b32 v1, v0
	buffer_inv sc1
	s_add_u32 s18, s34, 0xed10500
	s_addc_u32 s19, s35, 0
	v_mov_b32_e32 v0, 0
	s_mov_b32 s20, 0
	s_waitcnt lgkmcnt(0)
	v_cmp_eq_u32_e32 vcc, v200, v1
	s_cbranch_vccz .Lsb3_done

.LBB0_844:
	v_mov_b32_e32 v201, 0x24008
	ds_read_b32 v200, v201
	s_waitcnt lgkmcnt(0)
	s_cmp_lg_u32 s88, 0
	s_cbranch_scc1 .Lsl4_out
	s_cmp_lg_u32 s89, 18
	s_cbranch_scc1 .Lsl4_out
	s_load_dword s4, s[0:1], 0x120
	s_load_dwordx16 s[52:67], s[0:1], 0x0
	s_load_dwordx16 s[68:83], s[0:1], 0x80
	s_waitcnt lgkmcnt(0)
	s_add_u32 s98, s34, 0xed10500
	s_addc_u32 s99, s35, 0
	v_mov_b32_e32 v201, 0
	s_lshl_b32 s4, s4, 1
	s_mul_i32 s5, s4, 6
	s_lshl_b32 s33, s2, 1
	s_add_i32 s33, s33, s5
	s_mov_b32 s5, 7
	s_mul_i32 s4, s4, s5
	s_min_u32 s4, s4, 0x15d0
	s_cmp_ge_i32 s33, s4
	s_cbranch_scc1 .Lsl4_out
	s_add_u32 s94, s34, 0x1da0000
	s_addc_u32 s95, s35, 0
	v_writelane_b32 v252, s90, 0
	s_add_u32 s4, s34, 0x7a0000
	s_addc_u32 s5, s35, 0
	v_writelane_b32 v252, s91, 1
	v_writelane_b32 v252, s4, 2
	v_lshrrev_b32_e32 v138, 8, v204
	v_and_b32_e32 v139, 0xff, v204
	v_writelane_b32 v252, s5, 3
	s_add_u32 s4, s34, 0x720000
	s_addc_u32 s5, s35, 0
	v_writelane_b32 v252, s4, 4
	v_mul_u32_u24_e32 v140, 0x12000, v138
	v_mov_b32_e32 v129, 0
	v_writelane_b32 v252, s5, 5
	s_add_u32 s4, s34, 0x520000
	s_addc_u32 s5, s35, 0
	s_add_u32 s90, s34, 0x4a0000
	s_addc_u32 s91, s35, 0
	s_add_u32 s96, s34, 0x440000
	s_addc_u32 s97, s35, 0
	s_add_u32 s16, s34, 0x28a0000
	s_addc_u32 s17, s35, 0
	s_add_u32 s18, s0, 0x120
	v_writelane_b32 v252, s4, 6
	s_addc_u32 s19, s1, 0
	s_movk_i32 s8, 0x104
	s_movk_i32 s9, 0xffe0
	s_movk_i32 s10, 0x6000
	s_movk_i32 s11, 0x400
	s_mov_b32 s12, 0xbfb8aa3b
	s_mov_b32 s13, 0x42ce8ed0
	s_mov_b32 s14, 0xc2b17218
	s_movk_i32 s15, 0x1800
	v_mov_b32_e32 v141, 0xfffffd40
	v_mov_b32_e32 v142, 0xb00000
	v_mov_b32_e32 v143, 0x580000
	v_mov_b32_e32 v144, 0x7f800000
	v_writelane_b32 v252, s5, 7
	s_branch .Lsl4_22

.Lsl4_out:
	s_cmp_gt_i32 s88, 4
	s_cbranch_scc1 .Lsb4_skip
	s_cmp_lt_i32 s89, 6
	s_cbranch_scc1 .Lsb4_skip
	s_waitcnt vmcnt(0) lgkmcnt(0)
	s_and_saveexec_b64 s[16:17], s[92:93]
	s_cbranch_execz .Lsb4_done
	v_mov_b32_e32 v0, 0x24008
	ds_read_b32 v1, v0
	buffer_inv sc1
	s_add_u32 s18, s34, 0xed10500
	s_addc_u32 s19, s35, 0
	v_mov_b32_e32 v0, 0
	s_mov_b32 s20, 0
	s_waitcnt lgkmcnt(0)
	v_cmp_eq_u32_e32 vcc, v200, v1
	s_cbranch_vccz .Lsb4_done

.LBB0_1014:
	v_mov_b32_e32 v201, 0x24008
	ds_read_b32 v200, v201
	s_waitcnt lgkmcnt(0)
	s_cmp_lg_u32 s88, 0
	s_cbranch_scc1 .Lsl6_out
	s_cmp_lg_u32 s89, 18
	s_cbranch_scc1 .Lsl6_out
	s_load_dword s4, s[0:1], 0x120
	s_load_dwordx16 s[52:67], s[0:1], 0x0
	s_load_dwordx16 s[68:83], s[0:1], 0x80
	s_waitcnt lgkmcnt(0)
	s_add_u32 s98, s34, 0xed10500
	s_addc_u32 s99, s35, 0
	v_mov_b32_e32 v201, 0
	s_lshl_b32 s4, s4, 1
	s_mul_i32 s5, s4, 7
	s_lshl_b32 s33, s2, 1
	s_add_i32 s33, s33, s5
	s_mov_b32 s5, 8
	s_mul_i32 s4, s4, s5
	s_min_u32 s4, s4, 0x15d0
	s_cmp_ge_i32 s33, s4
	s_cbranch_scc1 .Lsl6_out
	s_add_u32 s94, s34, 0x1da0000
	s_addc_u32 s95, s35, 0
	v_writelane_b32 v252, s90, 0
	s_add_u32 s4, s34, 0x7a0000
	s_addc_u32 s5, s35, 0
	v_writelane_b32 v252, s91, 1
	v_writelane_b32 v252, s4, 2
	v_lshrrev_b32_e32 v138, 8, v204
	v_and_b32_e32 v139, 0xff, v204
	v_writelane_b32 v252, s5, 3
	s_add_u32 s4, s34, 0x720000
	s_addc_u32 s5, s35, 0
	v_writelane_b32 v252, s4, 4
	v_mul_u32_u24_e32 v140, 0x12000, v138
	v_mov_b32_e32 v129, 0
	v_writelane_b32 v252, s5, 5
	s_add_u32 s4, s34, 0x520000
	s_addc_u32 s5, s35, 0
	s_add_u32 s90, s34, 0x4a0000
	s_addc_u32 s91, s35, 0
	s_add_u32 s96, s34, 0x440000
	s_addc_u32 s97, s35, 0
	s_add_u32 s16, s34, 0x28a0000
	s_addc_u32 s17, s35, 0
	s_add_u32 s18, s0, 0x120
	v_writelane_b32 v252, s4, 6
	s_addc_u32 s19, s1, 0
	s_movk_i32 s8, 0x104
	s_movk_i32 s9, 0xffe0
	s_movk_i32 s10, 0x6000
	s_movk_i32 s11, 0x400
	s_mov_b32 s12, 0xbfb8aa3b
	s_mov_b32 s13, 0x42ce8ed0
	s_mov_b32 s14, 0xc2b17218
	s_movk_i32 s15, 0x1800
	v_mov_b32_e32 v141, 0xfffffd40
	v_mov_b32_e32 v142, 0xb00000
	v_mov_b32_e32 v143, 0x580000
	v_mov_b32_e32 v144, 0x7f800000
	v_writelane_b32 v252, s5, 7
	s_branch .Lsl6_22

.Lsl6_out:
	s_cmp_gt_i32 s88, 6
	s_cbranch_scc1 .Lsb6_skip
	s_cmp_lt_i32 s89, 8
	s_cbranch_scc1 .Lsb6_skip
	s_waitcnt vmcnt(0) lgkmcnt(0)
	s_and_saveexec_b64 s[16:17], s[92:93]
	s_cbranch_execz .Lsb6_done
	v_mov_b32_e32 v0, 0x24008
	ds_read_b32 v1, v0
	buffer_inv sc1
	s_add_u32 s18, s34, 0xed10500
	s_addc_u32 s19, s35, 0
	v_mov_b32_e32 v0, 0
	s_mov_b32 s20, 0
	s_waitcnt lgkmcnt(0)
	v_cmp_eq_u32_e32 vcc, v200, v1
	s_cbranch_vccz .Lsb6_done

.LBB0_1077:
	v_mov_b32_e32 v201, 0x24008
	ds_read_b32 v200, v201
	s_waitcnt lgkmcnt(0)
	s_cmp_lg_u32 s88, 0
	s_cbranch_scc1 .Lsl7_out
	s_cmp_lg_u32 s89, 18
	s_cbranch_scc1 .Lsl7_out
	s_load_dword s4, s[0:1], 0x120
	s_load_dwordx16 s[52:67], s[0:1], 0x0
	s_load_dwordx16 s[68:83], s[0:1], 0x80
	s_waitcnt lgkmcnt(0)
	s_add_u32 s98, s34, 0xed10500
	s_addc_u32 s99, s35, 0
	v_mov_b32_e32 v201, 0
	s_lshl_b32 s4, s4, 1
	s_mul_i32 s5, s4, 8
	s_lshl_b32 s33, s2, 1
	s_add_i32 s33, s33, s5
	s_mov_b32 s5, 9
	s_mul_i32 s4, s4, s5
	s_min_u32 s4, s4, 0x15d0
	s_cmp_ge_i32 s33, s4
	s_cbranch_scc1 .Lsl7_out
	s_add_u32 s94, s34, 0x1da0000
	s_addc_u32 s95, s35, 0
	v_writelane_b32 v252, s90, 0
	s_add_u32 s4, s34, 0x7a0000
	s_addc_u32 s5, s35, 0
	v_writelane_b32 v252, s91, 1
	v_writelane_b32 v252, s4, 2
	v_lshrrev_b32_e32 v138, 8, v204
	v_and_b32_e32 v139, 0xff, v204
	v_writelane_b32 v252, s5, 3
	s_add_u32 s4, s34, 0x720000
	s_addc_u32 s5, s35, 0
	v_writelane_b32 v252, s4, 4
	v_mul_u32_u24_e32 v140, 0x12000, v138
	v_mov_b32_e32 v129, 0
	v_writelane_b32 v252, s5, 5
	s_add_u32 s4, s34, 0x520000
	s_addc_u32 s5, s35, 0
	s_add_u32 s90, s34, 0x4a0000
	s_addc_u32 s91, s35, 0
	s_add_u32 s96, s34, 0x440000
	s_addc_u32 s97, s35, 0
	s_add_u32 s16, s34, 0x28a0000
	s_addc_u32 s17, s35, 0
	s_add_u32 s18, s0, 0x120
	v_writelane_b32 v252, s4, 6
	s_addc_u32 s19, s1, 0
	s_movk_i32 s8, 0x104
	s_movk_i32 s9, 0xffe0
	s_movk_i32 s10, 0x6000
	s_movk_i32 s11, 0x400
	s_mov_b32 s12, 0xbfb8aa3b
	s_mov_b32 s13, 0x42ce8ed0
	s_mov_b32 s14, 0xc2b17218
	s_movk_i32 s15, 0x1800
	v_mov_b32_e32 v141, 0xfffffd40
	v_mov_b32_e32 v142, 0xb00000
	v_mov_b32_e32 v143, 0x580000
	v_mov_b32_e32 v144, 0x7f800000
	v_writelane_b32 v252, s5, 7
	s_branch .Lsl7_22

.Lsl7_out:
	s_cmp_gt_i32 s88, 7
	s_cbranch_scc1 .Lsb7_skip
	s_cmp_lt_i32 s89, 9
	s_cbranch_scc1 .Lsb7_skip
	s_waitcnt vmcnt(0) lgkmcnt(0)
	s_and_saveexec_b64 s[16:17], s[92:93]
	s_cbranch_execz .Lsb7_done
	v_mov_b32_e32 v0, 0x24008
	ds_read_b32 v1, v0
	buffer_inv sc1
	s_add_u32 s18, s34, 0xed10500
	s_addc_u32 s19, s35, 0
	v_mov_b32_e32 v0, 0
	s_mov_b32 s20, 0
	s_waitcnt lgkmcnt(0)
	v_cmp_eq_u32_e32 vcc, v200, v1
	s_cbranch_vccz .Lsb7_done

.LBB0_1140:
	v_mov_b32_e32 v201, 0x24008
	ds_read_b32 v200, v201
	s_waitcnt lgkmcnt(0)
	s_cmp_lg_u32 s88, 0
	s_cbranch_scc1 .Lsl8_out
	s_cmp_lg_u32 s89, 18
	s_cbranch_scc1 .Lsl8_out
	s_load_dword s4, s[0:1], 0x120
	s_load_dwordx16 s[52:67], s[0:1], 0x0
	s_load_dwordx16 s[68:83], s[0:1], 0x80
	s_waitcnt lgkmcnt(0)
	s_add_u32 s98, s34, 0xed10500
	s_addc_u32 s99, s35, 0
	v_mov_b32_e32 v201, 0
	s_lshl_b32 s4, s4, 1
	s_mul_i32 s5, s4, 9
	s_lshl_b32 s33, s2, 1
	s_add_i32 s33, s33, s5
	s_mov_b32 s5, 10
	s_mul_i32 s4, s4, s5
	s_min_u32 s4, s4, 0x15d0
	s_cmp_ge_i32 s33, s4
	s_cbranch_scc1 .Lsl8_out
	s_add_u32 s94, s34, 0x1da0000
	s_addc_u32 s95, s35, 0
	v_writelane_b32 v252, s90, 0
	s_add_u32 s4, s34, 0x7a0000
	s_addc_u32 s5, s35, 0
	v_writelane_b32 v252, s91, 1
	v_writelane_b32 v252, s4, 2
	v_lshrrev_b32_e32 v138, 8, v204
	v_and_b32_e32 v139, 0xff, v204
	v_writelane_b32 v252, s5, 3
	s_add_u32 s4, s34, 0x720000
	s_addc_u32 s5, s35, 0
	v_writelane_b32 v252, s4, 4
	v_mul_u32_u24_e32 v140, 0x12000, v138
	v_mov_b32_e32 v129, 0
	v_writelane_b32 v252, s5, 5
	s_add_u32 s4, s34, 0x520000
	s_addc_u32 s5, s35, 0
	s_add_u32 s90, s34, 0x4a0000
	s_addc_u32 s91, s35, 0
	s_add_u32 s96, s34, 0x440000
	s_addc_u32 s97, s35, 0
	s_add_u32 s16, s34, 0x28a0000
	s_addc_u32 s17, s35, 0
	s_add_u32 s18, s0, 0x120
	v_writelane_b32 v252, s4, 6
	s_addc_u32 s19, s1, 0
	s_movk_i32 s8, 0x104
	s_movk_i32 s9, 0xffe0
	s_movk_i32 s10, 0x6000
	s_movk_i32 s11, 0x400
	s_mov_b32 s12, 0xbfb8aa3b
	s_mov_b32 s13, 0x42ce8ed0
	s_mov_b32 s14, 0xc2b17218
	s_movk_i32 s15, 0x1800
	v_mov_b32_e32 v141, 0xfffffd40
	v_mov_b32_e32 v142, 0xb00000
	v_mov_b32_e32 v143, 0x580000
	v_mov_b32_e32 v144, 0x7f800000
	v_writelane_b32 v252, s5, 7
	s_branch .Lsl8_22

.Lsl8_out:
	s_cmp_gt_i32 s88, 8
	s_cbranch_scc1 .Lsb8_skip
	s_cmp_lt_i32 s89, 10
	s_cbranch_scc1 .Lsb8_skip
	s_waitcnt vmcnt(0) lgkmcnt(0)
	s_and_saveexec_b64 s[16:17], s[92:93]
	s_cbranch_execz .Lsb8_done
	v_mov_b32_e32 v0, 0x24008
	ds_read_b32 v1, v0
	buffer_inv sc1
	s_add_u32 s18, s34, 0xed10500
	s_addc_u32 s19, s35, 0
	v_mov_b32_e32 v0, 0
	s_mov_b32 s20, 0
	s_waitcnt lgkmcnt(0)
	v_cmp_eq_u32_e32 vcc, v200, v1
	s_cbranch_vccz .Lsb8_done

.LBB0_1202:
	v_mov_b32_e32 v201, 0x24008
	ds_read_b32 v200, v201
	s_waitcnt lgkmcnt(0)
	s_cmp_lg_u32 s88, 0
	s_cbranch_scc1 .Lsl9_out
	s_cmp_lg_u32 s89, 18
	s_cbranch_scc1 .Lsl9_out
	s_load_dword s4, s[0:1], 0x120
	s_load_dwordx16 s[52:67], s[0:1], 0x0
	s_load_dwordx16 s[68:83], s[0:1], 0x80
	s_waitcnt lgkmcnt(0)
	s_add_u32 s98, s34, 0xed10500
	s_addc_u32 s99, s35, 0
	v_mov_b32_e32 v201, 0
	s_lshl_b32 s4, s4, 1
	s_mul_i32 s5, s4, 10
	s_lshl_b32 s33, s2, 1
	s_add_i32 s33, s33, s5
	s_mov_b32 s5, 11
	s_mul_i32 s4, s4, s5
	s_min_u32 s4, s4, 0x15d0
	s_cmp_ge_i32 s33, s4
	s_cbranch_scc1 .Lsl9_out
	s_add_u32 s94, s34, 0x1da0000
	s_addc_u32 s95, s35, 0
	v_writelane_b32 v252, s90, 0
	s_add_u32 s4, s34, 0x7a0000
	s_addc_u32 s5, s35, 0
	v_writelane_b32 v252, s91, 1
	v_writelane_b32 v252, s4, 2
	v_lshrrev_b32_e32 v138, 8, v204
	v_and_b32_e32 v139, 0xff, v204
	v_writelane_b32 v252, s5, 3
	s_add_u32 s4, s34, 0x720000
	s_addc_u32 s5, s35, 0
	v_writelane_b32 v252, s4, 4
	v_mul_u32_u24_e32 v140, 0x12000, v138
	v_mov_b32_e32 v129, 0
	v_writelane_b32 v252, s5, 5
	s_add_u32 s4, s34, 0x520000
	s_addc_u32 s5, s35, 0
	s_add_u32 s90, s34, 0x4a0000
	s_addc_u32 s91, s35, 0
	s_add_u32 s96, s34, 0x440000
	s_addc_u32 s97, s35, 0
	s_add_u32 s16, s34, 0x28a0000
	s_addc_u32 s17, s35, 0
	s_add_u32 s18, s0, 0x120
	v_writelane_b32 v252, s4, 6
	s_addc_u32 s19, s1, 0
	s_movk_i32 s8, 0x104
	s_movk_i32 s9, 0xffe0
	s_movk_i32 s10, 0x6000
	s_movk_i32 s11, 0x400
	s_mov_b32 s12, 0xbfb8aa3b
	s_mov_b32 s13, 0x42ce8ed0
	s_mov_b32 s14, 0xc2b17218
	s_movk_i32 s15, 0x1800
	v_mov_b32_e32 v141, 0xfffffd40
	v_mov_b32_e32 v142, 0xb00000
	v_mov_b32_e32 v143, 0x580000
	v_mov_b32_e32 v144, 0x7f800000
	v_writelane_b32 v252, s5, 7
	s_branch .Lsl9_22

.Lsl9_out:
	s_cmp_gt_i32 s88, 9
	s_cbranch_scc1 .Lsb9_skip
	s_cmp_lt_i32 s89, 11
	s_cbranch_scc1 .Lsb9_skip
	s_waitcnt vmcnt(0) lgkmcnt(0)
	s_and_saveexec_b64 s[16:17], s[92:93]
	s_cbranch_execz .Lsb9_done
	v_mov_b32_e32 v0, 0x24008
	ds_read_b32 v1, v0
	buffer_inv sc1
	s_add_u32 s18, s34, 0xed10500
	s_addc_u32 s19, s35, 0
	v_mov_b32_e32 v0, 0
	s_mov_b32 s20, 0
	s_waitcnt lgkmcnt(0)
	v_cmp_eq_u32_e32 vcc, v200, v1
	s_cbranch_vccz .Lsb9_done
